# P7 lora-output GEMM skips the structurally zero K-tiles of W2 (per-unit K start and trip count): exact, same bf16 MFMA
# speedup vs baseline: 1.0357x; 1.0357x over previous
; #define PG8_STAGE(bufoff, gbase, voff) do { _Pragma("unroll") for (int _i = 0; _i < 2; ++_i) \
;         __builtin_amdgcn_global_load_lds((const unsigned*)((const char*)(gbase) + (voff)[_i]), (PG8_LAS unsigned*)(lds + (bufoff) + ldsw + _i * 8192), 16, 0, 0); } while (0)
; #define PG8_WAIT_V(n) asm volatile("s_waitcnt vmcnt(" #n ")" ::: "memory")
; #define PG8_BAR __builtin_amdgcn_s_barrier()
; template <class Epi, class Sched, bool ALIGN_EPI = false, bool SP2 = false>
; __device__ __forceinline__ void gemm_phase(PG8_LAS unsigned char* lds, const Gemm g, const Sched& S, const Epi& E) {
;     ...
;     for (int i = 0; i < 2; ++i) { int R, C; stage_rc(tid * 16 + i * 8192, R, C); const int Rb = Epi::PERM ? ((R & ~31) + perm32(R & 31)) : R;
;         voffA[i] = (unsigned)(R * K + C) * 2u; voffB[i] = (unsigned)(Rb * K + C) * 2u; }
;     const size_t kstep = (size_t)(BK * 2);
;     const size_t hstep = (size_t)HALF * K * 2;
;     const size_t tstep = 2 * hstep;
;     const unsigned ldsw = (unsigned)wid * 1024u;
;     const int aoff = lds_byte(wr * 64 + fr, fq * 8), boff = lds_byte(wc * 32 + fr, fq * 8);
;     ...
;     const char* cA = (const char*)g.A + (size_t)cur.pm * tstep; const char* cB = (const char*)g.Bt + (size_t)cur.pn * tstep;
;     S.a_ready(cur);
;     if constexpr (SP2) {
;         PG8_STAGE(PG8_SB(0, 0), cB, voffB); PG8_STAGE(PG8_SB(0, 1), cB + hstep, voffB); PG8_STAGE(PG8_SA(0, 0), cA, voffA); PG8_STAGE(PG8_SA(0, 1), cA + hstep, voffA);
;         if (wr == 1) PG8_BAR;
;         PG8_WAIT_V(2); PG8_BAR;
;         PG8_STAGE(PG8_SB(1, 0), cB + kstep, voffB); PG8_STAGE(PG8_SA(1, 0), cA + kstep, voffA); PG8_STAGE(PG8_SB(1, 1), cB + hstep + kstep, voffB);
;         PG8_WAIT_V(6); PG8_BAR;
.LBB0_853:
	s_waitcnt vmcnt(0)
	s_cmp_gt_i32 s33, 7
	s_cselect_b32 s99, 0x100, 0
	v_lshrrev_b32_e32 v4, 1, v172
	v_and_b32_e32 v12, 24, v4
	v_lshrrev_b32_e32 v4, 5, v172
	s_add_u32 s38, s92, 0x16200000
	v_and_b32_e32 v4, 4, v4
	v_bfe_u32 v5, v172, 2, 2
	s_addc_u32 s39, s93, 0
	v_lshlrev_b32_e32 v1, 4, v172
	v_and_b32_e32 v2, 32, v172
	v_bfe_u32 v3, v172, 2, 4
	v_or3_b32 v4, v4, v5, v12
	v_lshrrev_b32_e32 v5, 3, v172
	s_movk_i32 s0, 0x70
	s_add_u32 s40, s92, 0x1800000
	v_bitop3_b32 v10, v1, v2, 48 bitop3:0x6c
	v_and_or_b32 v6, v5, s0, v3
	s_movk_i32 s0, 0x60
	v_add_u32_e32 v1, 0x2000, v1
	s_addc_u32 s41, s93, 0
	v_and_b32_e32 v11, 64, v172
	v_and_or_b32 v5, v5, s0, v4
	v_lshrrev_b32_e32 v1, 7, v1
	s_movk_i32 s0, 0xf0
	s_lshr_b32 s4, s2, 6
	s_lshr_b32 s3, s2, 8
	v_or_b32_e32 v2, v10, v11
	v_and_or_b32 v3, v1, s0, v3
	s_movk_i32 s0, 0xe0
	s_lshl_b32 s42, s4, 10
	s_mul_i32 s1, s33, 0x30000
	v_lshrrev_b32_e32 v2, 1, v2
	v_mul_u32_u24_e32 v5, 0x180, v5
	v_and_or_b32 v1, v1, s0, v4
	s_mul_hi_i32 s0, s33, 0x30000
	s_add_u32 s6, s40, s1
	v_or_b32_e32 v5, v5, v2
	s_addc_u32 s7, s41, s0
	s_add_u32 s6, s6, s99
	s_addc_u32 s7, s7, 0
	s_add_i32 s43, s42, 0
	v_lshlrev_b32_e32 v132, 1, v5
	v_mul_u32_u24_e32 v1, 0x180, v1
	s_add_i32 m0, s43, 0x10000
	v_or_b32_e32 v1, v1, v2
	global_load_lds_dwordx4 v132, s[6:7]
	s_add_i32 m0, s43, 0x12000
	v_lshlrev_b32_e32 v136, 1, v1
	s_add_u32 s0, s6, 0x18000
	global_load_lds_dwordx4 v136, s[6:7]
	s_addc_u32 s1, s7, 0
	s_add_i32 m0, s43, 0x14000
	s_mul_i32 s8, s34, 0x30000
	global_load_lds_dwordx4 v132, s[0:1]
	s_add_i32 m0, s43, 0x16000
	v_mul_u32_u24_e32 v13, 0x180, v6
	s_mul_hi_i32 s5, s34, 0x30000
	s_add_u32 s8, s38, s8
	v_or_b32_e32 v6, v2, v13
	v_mul_u32_u24_e32 v14, 0x180, v3
	s_addc_u32 s9, s39, s5
	s_add_u32 s8, s8, s99
	s_addc_u32 s9, s9, 0
	s_add_i32 s44, s43, 0x2000
	v_lshlrev_b32_e32 v130, 1, v6
	v_or_b32_e32 v3, v14, v2
	global_load_lds_dwordx4 v136, s[0:1]
	s_mov_b32 m0, s43
	s_add_u32 s0, s8, 0x18000
	v_lshlrev_b32_e32 v134, 1, v3
	global_load_lds_dwordx4 v130, s[8:9]
	s_mov_b32 m0, s44
	s_addc_u32 s1, s9, 0
	s_add_i32 s45, s43, 0x4000
	global_load_lds_dwordx4 v134, s[8:9]
	s_mov_b32 m0, s45
	s_add_i32 s52, s43, 0x6000
	global_load_lds_dwordx4 v130, s[0:1]
	s_mov_b32 m0, s52
	v_mov_b32_e32 v139, 0
	global_load_lds_dwordx4 v134, s[0:1]
	v_mov_b32_e32 v133, v139
	v_mov_b32_e32 v137, v139
	v_mov_b32_e32 v131, v139
	v_mov_b32_e32 v135, v139
	s_cmp_eq_u32 s3, 1
	s_mov_b32 s53, 0
	v_lshl_add_u64 v[8:9], s[6:7], 0, v[132:133]
	v_lshl_add_u64 v[6:7], s[6:7], 0, v[136:137]
	v_lshl_add_u64 v[2:3], s[8:9], 0, v[130:131]
	s_cselect_b64 s[0:1], -1, 0
	s_cmp_lg_u32 s3, 1
	v_lshl_add_u64 v[4:5], s[8:9], 0, v[134:135]
	s_cbranch_scc1 .LBB0_855
	s_barrier

; #define PG8_STAGE(bufoff, gbase, voff) do { _Pragma("unroll") for (int _i = 0; _i < 2; ++_i) \
;         __builtin_amdgcn_global_load_lds((const unsigned*)((const char*)(gbase) + (voff)[_i]), (PG8_LAS unsigned*)(lds + (bufoff) + ldsw + _i * 8192), 16, 0, 0); } while (0)
; #define PG8_LDA(dst, b, h) do { _Pragma("unroll") for (int m = 0; m < 4; ++m) _Pragma("unroll") for (int k = 0; k < 2; ++k) dst[m][k] = *(const PG8_LAS bf16x8*)(lds + PG8_SA(b, h) + aoff + m * 2048 + k * 1024); } while (0)
; #define PG8_LDB(dst, b, h) do { _Pragma("unroll") for (int n = 0; n < 2; ++n) _Pragma("unroll") for (int k = 0; k < 2; ++k) dst[n][k] = *(const PG8_LAS bf16x8*)(lds + PG8_SB(b, h) + boff + n * 2048 + k * 1024); } while (0)
; #define PG8_WAIT_V(n) asm volatile("s_waitcnt vmcnt(" #n ")" ::: "memory")
; #define PG8_WAIT_L(n) asm volatile("s_waitcnt lgkmcnt(" #n ")" ::: "memory")
; #define PG8_BAR __builtin_amdgcn_s_barrier()
; #define PG8_SCHED __builtin_amdgcn_sched_barrier(0)
; template <class Epi, class Sched, bool ALIGN_EPI = false, bool SP2 = false>
; __device__ __forceinline__ void gemm_phase(PG8_LAS unsigned char* lds, const Gemm g, const Sched& S, const Epi& E) {
;     ...
;         const bool has_next = S.next(ui + 1, nxt);
;         const char* nA = has_next ? (const char*)g.A + (size_t)nxt.pm * tstep : cA; const char* nB = has_next ? (const char*)g.Bt + (size_t)nxt.pn * tstep : cB;
; #pragma nounroll
;         for (int t = 0; t < nt; t += 2) {
;             const bool last = (t == nt - 2);
;             const char* a1 = cA + (size_t)(t + 1) * kstep;
;             const char* a2 = last ? nA : cA + (size_t)(t + 2) * kstep; const char* b2 = last ? nB : cB + (size_t)(t + 2) * kstep;
;             const char* a3 = a2 + kstep; const char* b3 = b2 + kstep;
;             if (last && has_next) S.a_ready(nxt);
;             if constexpr (SP2) {
;             PG8_LDB(B0, 0, 0); PG8_LDB(B1, 0, 1); PG8_SCHED; PG8_LDA(At, 0, 0); PG8_STAGE(PG8_SA(1, 1), a1 + hstep, voffA);
;             PG8_WAIT_V(8); PG8_WAIT_L(0); PG8_BAR; PG8_MMA(0, 0, At, B0); PG8_MMA(0, 1, At, B1); PG8_BAR; PG8_SCHED;
;     ...
; #pragma unroll
;         for (int a = 0; a < 2; ++a)
; #pragma unroll
;             for (int b = 0; b < 2; ++b)
; #pragma unroll
;                 for (int m = 0; m < 4; ++m)
; #pragma unroll
;                     for (int n = 0; n < 2; ++n) acc[a][b][m][n] = (f32x4){0.f, 0.f, 0.f, 0.f};
.LBB0_860:
	s_nop 0
	v_cndmask_b32_e64 v2, 0, 1, s[4:5]
	v_cmp_ne_u32_e64 s[2:3], 1, v2
	s_andn2_b64 vcc, exec, s[4:5]
	s_mov_b64 s[28:29], s[8:9]
	s_cbranch_vccnz .LBB0_862
	s_mul_i32 s5, s69, 0x30000
	s_mul_hi_i32 s4, s69, 0x30000
	s_add_u32 s28, s38, s5
	s_addc_u32 s29, s39, s4
	s_cmp_gt_i32 s68, 7
	s_cselect_b32 s100, 0x100, 0
	s_add_u32 s28, s28, s100
	s_addc_u32 s29, s29, 0
.LBB0_862:
	s_and_b64 vcc, exec, s[2:3]
	s_mov_b64 s[30:31], s[6:7]
	s_cbranch_vccnz .LBB0_864
	s_mul_i32 s5, s68, 0x30000
	s_mul_hi_i32 s4, s68, 0x30000
	s_add_u32 s30, s40, s5
	s_addc_u32 s31, s41, s4
	s_cmp_gt_i32 s68, 7
	s_cselect_b32 s100, 0x100, 0
	s_add_u32 s30, s30, s100
	s_addc_u32 s31, s31, 0
.LBB0_864:
	s_cmp_gt_i32 s33, 7
	s_cselect_b32 s98, 2, 0
	s_add_i32 s101, s98, -2
	s_add_u32 s4, s8, 0x18080
	s_addc_u32 s5, s9, 0
	s_add_u32 s35, s6, 0x100
	v_mov_b32_e32 v2, 0
	s_addc_u32 s70, s7, 0
	s_mov_b32 s71, -2
	v_mov_b32_e32 v3, v2
	v_mov_b32_e32 v4, v2
	v_mov_b32_e32 v5, v2
	v_mov_b32_e32 v6, v2
	v_mov_b32_e32 v7, v2
	v_mov_b32_e32 v8, v2
	v_mov_b32_e32 v9, v2
	v_mov_b32_e32 v18, v2
	v_mov_b32_e32 v19, v2
	v_mov_b32_e32 v20, v2
	v_mov_b32_e32 v21, v2
	v_mov_b32_e32 v22, v2
	v_mov_b32_e32 v23, v2
	v_mov_b32_e32 v24, v2
	v_mov_b32_e32 v25, v2
	v_mov_b32_e32 v34, v2
	v_mov_b32_e32 v35, v2
	v_mov_b32_e32 v36, v2
	v_mov_b32_e32 v37, v2
	v_mov_b32_e32 v38, v2
	v_mov_b32_e32 v39, v2
	v_mov_b32_e32 v40, v2
	v_mov_b32_e32 v41, v2
	v_mov_b32_e32 v50, v2
	v_mov_b32_e32 v51, v2
	v_mov_b32_e32 v52, v2
	v_mov_b32_e32 v53, v2
	v_mov_b32_e32 v54, v2
	v_mov_b32_e32 v55, v2
	v_mov_b32_e32 v56, v2
	v_mov_b32_e32 v57, v2
	v_mov_b32_e32 v10, v2
	v_mov_b32_e32 v11, v2
	v_mov_b32_e32 v12, v2
	v_mov_b32_e32 v13, v2
	v_mov_b32_e32 v14, v2
	v_mov_b32_e32 v15, v2
	v_mov_b32_e32 v16, v2
	v_mov_b32_e32 v17, v2
	v_mov_b32_e32 v26, v2
	v_mov_b32_e32 v27, v2
	v_mov_b32_e32 v28, v2
	v_mov_b32_e32 v29, v2
	v_mov_b32_e32 v30, v2
	v_mov_b32_e32 v31, v2
	v_mov_b32_e32 v32, v2
	v_mov_b32_e32 v33, v2
	v_mov_b32_e32 v42, v2
	v_mov_b32_e32 v43, v2
	v_mov_b32_e32 v44, v2
	v_mov_b32_e32 v45, v2
	v_mov_b32_e32 v46, v2
	v_mov_b32_e32 v47, v2
	v_mov_b32_e32 v48, v2
	v_mov_b32_e32 v49, v2
	v_mov_b32_e32 v58, v2
	v_mov_b32_e32 v59, v2
	v_mov_b32_e32 v60, v2
	v_mov_b32_e32 v61, v2
	v_mov_b32_e32 v62, v2
	v_mov_b32_e32 v63, v2
	v_mov_b32_e32 v64, v2
	v_mov_b32_e32 v65, v2
	v_mov_b32_e32 v66, v2
	v_mov_b32_e32 v67, v2
	v_mov_b32_e32 v68, v2
	v_mov_b32_e32 v69, v2
	v_mov_b32_e32 v70, v2
	v_mov_b32_e32 v71, v2
	v_mov_b32_e32 v72, v2
	v_mov_b32_e32 v73, v2
	v_mov_b32_e32 v82, v2
	v_mov_b32_e32 v83, v2
	v_mov_b32_e32 v84, v2
	v_mov_b32_e32 v85, v2
	v_mov_b32_e32 v86, v2
	v_mov_b32_e32 v87, v2
	v_mov_b32_e32 v88, v2
	v_mov_b32_e32 v89, v2
	v_mov_b32_e32 v98, v2
	v_mov_b32_e32 v99, v2
	v_mov_b32_e32 v100, v2
	v_mov_b32_e32 v101, v2
	v_mov_b32_e32 v102, v2
	v_mov_b32_e32 v103, v2
	v_mov_b32_e32 v104, v2
	v_mov_b32_e32 v105, v2
	v_mov_b32_e32 v114, v2
	v_mov_b32_e32 v115, v2
	v_mov_b32_e32 v116, v2
	v_mov_b32_e32 v117, v2
	v_mov_b32_e32 v118, v2
	v_mov_b32_e32 v119, v2
	v_mov_b32_e32 v120, v2
	v_mov_b32_e32 v121, v2
	v_mov_b32_e32 v74, v2
	v_mov_b32_e32 v75, v2
	v_mov_b32_e32 v76, v2
	v_mov_b32_e32 v77, v2
	v_mov_b32_e32 v78, v2
	v_mov_b32_e32 v79, v2
	v_mov_b32_e32 v80, v2
	v_mov_b32_e32 v81, v2
	v_mov_b32_e32 v90, v2
	v_mov_b32_e32 v91, v2
	v_mov_b32_e32 v92, v2
	v_mov_b32_e32 v93, v2
	v_mov_b32_e32 v94, v2
	v_mov_b32_e32 v95, v2
	v_mov_b32_e32 v96, v2
	v_mov_b32_e32 v97, v2
	v_mov_b32_e32 v106, v2
	v_mov_b32_e32 v107, v2
	v_mov_b32_e32 v108, v2
	v_mov_b32_e32 v109, v2
	v_mov_b32_e32 v110, v2
	v_mov_b32_e32 v111, v2
	v_mov_b32_e32 v112, v2
	v_mov_b32_e32 v113, v2
	v_mov_b32_e32 v122, v2
	v_mov_b32_e32 v123, v2
	v_mov_b32_e32 v124, v2
	v_mov_b32_e32 v125, v2
	v_mov_b32_e32 v126, v2
	v_mov_b32_e32 v127, v2
	v_mov_b32_e32 v128, v2
	v_mov_b32_e32 v129, v2
.LBB0_865:
	ds_read_b128 v[148:151], v170
	ds_read_b128 v[152:155], v170 offset:1024
	ds_read_b128 v[156:159], v170 offset:2048
	ds_read_b128 v[160:163], v170 offset:3072
	ds_read_b128 v[164:167], v171
	ds_read_b128 v[176:179], v171 offset:1024
	ds_read_b128 v[180:183], v171 offset:2048
	ds_read_b128 v[184:187], v171 offset:3072
	s_add_u32 s6, s4, 0xfffe8080
	s_addc_u32 s7, s5, -1
	s_cmp_eq_u32 s71, s101
	s_cselect_b32 s9, s29, s7
	s_cselect_b32 s8, s28, s6
	s_cselect_b32 s7, s31, s70
	s_cselect_b32 s6, s30, s35
	v_lshl_add_u64 v[220:221], s[4:5], 0, v[140:141]
	s_add_i32 m0, s43, 0xc000
	ds_read_b128 v[188:191], v174
	ds_read_b128 v[192:195], v174 offset:1024
	ds_read_b128 v[196:199], v174 offset:2048
	ds_read_b128 v[200:203], v174 offset:3072
	ds_read_b128 v[204:207], v174 offset:4096
	ds_read_b128 v[208:211], v174 offset:5120
	ds_read_b128 v[212:215], v174 offset:6144
	ds_read_b128 v[216:219], v174 offset:7168
	global_load_lds_dwordx4 v[220:221], off
	v_lshl_add_u64 v[220:221], s[4:5], 0, v[142:143]
	s_add_i32 m0, s43, 0xe000
	s_nop 0
	global_load_lds_dwordx4 v[220:221], off
	s_waitcnt vmcnt(8)
	s_waitcnt lgkmcnt(0)
	s_barrier
; #define PG8_STAGE(bufoff, gbase, voff) do { _Pragma("unroll") for (int _i = 0; _i < 2; ++_i) \
;         __builtin_amdgcn_global_load_lds((const unsigned*)((const char*)(gbase) + (voff)[_i]), (PG8_LAS unsigned*)(lds + (bufoff) + ldsw + _i * 8192), 16, 0, 0); } while (0)
; #define PG8_LDA(dst, b, h) do { _Pragma("unroll") for (int m = 0; m < 4; ++m) _Pragma("unroll") for (int k = 0; k < 2; ++k) dst[m][k] = *(const PG8_LAS bf16x8*)(lds + PG8_SA(b, h) + aoff + m * 2048 + k * 1024); } while (0)
; #define PG8_MMA(ai, bj, At, Bt) do { __builtin_amdgcn_s_setprio(1); _Pragma("unroll") for (int m = 0; m < 4; ++m) _Pragma("unroll") for (int n = 0; n < 2; ++n) _Pragma("unroll") for (int k = 0; k < 2; ++k) \
;         acc[ai][bj][m][n] = __builtin_amdgcn_mfma_f32_16x16x32_bf16(Bt[n][k], At[m][k], acc[ai][bj][m][n], 0, 0, 0); __builtin_amdgcn_s_setprio(0); } while (0)
; #define PG8_WAIT_V(n) asm volatile("s_waitcnt vmcnt(" #n ")" ::: "memory")
; #define PG8_WAIT_L(n) asm volatile("s_waitcnt lgkmcnt(" #n ")" ::: "memory")
; #define PG8_BAR __builtin_amdgcn_s_barrier()
; #define PG8_SCHED __builtin_amdgcn_sched_barrier(0)
; template <class Epi, class Sched, bool ALIGN_EPI = false, bool SP2 = false>
; __device__ __forceinline__ void gemm_phase(PG8_LAS unsigned char* lds, const Gemm g, const Sched& S, const Epi& E) {
;     ...
;             PG8_WAIT_V(8); PG8_WAIT_L(0); PG8_BAR; PG8_MMA(0, 0, At, B0); PG8_MMA(0, 1, At, B1); PG8_BAR; PG8_SCHED;
;             PG8_LDA(At, 0, 1); PG8_STAGE(PG8_SB(0, 0), b2, voffB); PG8_STAGE(PG8_SB(0, 1), b2 + hstep, voffB); PG8_STAGE(PG8_SA(0, 0), a2, voffA);
;             PG8_WAIT_V(8); PG8_WAIT_L(0); PG8_BAR; PG8_MMA(1, 0, At, B0); PG8_MMA(1, 1, At, B1); PG8_BAR; PG8_SCHED;
	s_setprio 1
	s_waitcnt lgkmcnt(0)
	v_mfma_f32_16x16x32_bf16 v[126:129], v[148:151], v[188:191], v[126:129]
	v_mfma_f32_16x16x32_bf16 v[122:125], v[156:159], v[188:191], v[122:125]
	v_mfma_f32_16x16x32_bf16 v[110:113], v[148:151], v[196:199], v[110:113]
	v_mfma_f32_16x16x32_bf16 v[106:109], v[156:159], v[196:199], v[106:109]
	v_mfma_f32_16x16x32_bf16 v[94:97], v[148:151], v[204:207], v[94:97]
	v_mfma_f32_16x16x32_bf16 v[90:93], v[156:159], v[204:207], v[90:93]
	v_mfma_f32_16x16x32_bf16 v[78:81], v[148:151], v[212:215], v[78:81]
	v_mfma_f32_16x16x32_bf16 v[74:77], v[156:159], v[212:215], v[74:77]
	v_mfma_f32_16x16x32_bf16 v[126:129], v[152:155], v[192:195], v[126:129]
	v_mfma_f32_16x16x32_bf16 v[122:125], v[160:163], v[192:195], v[122:125]
	v_mfma_f32_16x16x32_bf16 v[110:113], v[152:155], v[200:203], v[110:113]
	v_mfma_f32_16x16x32_bf16 v[106:109], v[160:163], v[200:203], v[106:109]
	v_mfma_f32_16x16x32_bf16 v[94:97], v[152:155], v[208:211], v[94:97]
	v_mfma_f32_16x16x32_bf16 v[90:93], v[160:163], v[208:211], v[90:93]
	v_mfma_f32_16x16x32_bf16 v[78:81], v[152:155], v[216:219], v[78:81]
	v_mfma_f32_16x16x32_bf16 v[74:77], v[160:163], v[216:219], v[74:77]
	s_setprio 0
	s_setprio 1
	v_mfma_f32_16x16x32_bf16 v[118:121], v[164:167], v[188:191], v[118:121]
	v_mfma_f32_16x16x32_bf16 v[114:117], v[180:183], v[188:191], v[114:117]
	v_mfma_f32_16x16x32_bf16 v[102:105], v[164:167], v[196:199], v[102:105]
	v_mfma_f32_16x16x32_bf16 v[98:101], v[180:183], v[196:199], v[98:101]
	v_mfma_f32_16x16x32_bf16 v[86:89], v[164:167], v[204:207], v[86:89]
	v_mfma_f32_16x16x32_bf16 v[82:85], v[180:183], v[204:207], v[82:85]
	v_mfma_f32_16x16x32_bf16 v[70:73], v[164:167], v[212:215], v[70:73]
	v_mfma_f32_16x16x32_bf16 v[66:69], v[180:183], v[212:215], v[66:69]
	v_mfma_f32_16x16x32_bf16 v[118:121], v[176:179], v[192:195], v[118:121]
	v_mfma_f32_16x16x32_bf16 v[114:117], v[184:187], v[192:195], v[114:117]
	v_mfma_f32_16x16x32_bf16 v[102:105], v[176:179], v[200:203], v[102:105]
	v_mfma_f32_16x16x32_bf16 v[98:101], v[184:187], v[200:203], v[98:101]
	v_mfma_f32_16x16x32_bf16 v[86:89], v[176:179], v[208:211], v[86:89]
	v_mfma_f32_16x16x32_bf16 v[82:85], v[184:187], v[208:211], v[82:85]
	v_mfma_f32_16x16x32_bf16 v[70:73], v[176:179], v[216:219], v[70:73]
	v_mfma_f32_16x16x32_bf16 v[66:69], v[184:187], v[216:219], v[66:69]
	s_setprio 0
	s_barrier
	s_add_i32 s72, s66, s42
	v_lshl_add_u64 v[220:221], s[6:7], 0, v[132:133]
	s_mov_b32 m0, s72
	ds_read_b128 v[188:191], v174 offset:16384
	ds_read_b128 v[192:195], v174 offset:17408
	ds_read_b128 v[196:199], v174 offset:18432
	ds_read_b128 v[200:203], v174 offset:19456
	ds_read_b128 v[204:207], v174 offset:20480
	ds_read_b128 v[208:211], v174 offset:21504
	ds_read_b128 v[212:215], v174 offset:22528
	ds_read_b128 v[216:219], v174 offset:23552
	global_load_lds_dwordx4 v[220:221], off
	s_add_i32 m0, s72, 0x2000
	s_add_u32 s72, s6, 0x18000
	v_lshl_add_u64 v[222:223], s[6:7], 0, v[136:137]
	s_addc_u32 s73, s7, 0
	s_add_i32 s74, s67, s42
	global_load_lds_dwordx4 v[222:223], off
	v_lshl_add_u64 v[224:225], s[72:73], 0, v[132:133]
	s_mov_b32 m0, s74
	v_lshl_add_u64 v[226:227], s[8:9], 0, v[134:135]
	global_load_lds_dwordx4 v[224:225], off
	v_lshl_add_u64 v[224:225], s[72:73], 0, v[136:137]
	s_add_i32 m0, s74, 0x2000
	s_nop 0
	global_load_lds_dwordx4 v[224:225], off
	v_lshl_add_u64 v[224:225], s[8:9], 0, v[130:131]
	s_mov_b32 m0, s43
	s_nop 0
	global_load_lds_dwordx4 v[224:225], off
	s_mov_b32 m0, s44
	s_nop 0
	global_load_lds_dwordx4 v[226:227], off
	s_waitcnt vmcnt(8)
	s_waitcnt lgkmcnt(0)
	s_barrier
	s_setprio 1
	s_waitcnt lgkmcnt(0)
	v_mfma_f32_16x16x32_bf16 v[62:65], v[148:151], v[188:191], v[62:65]
	v_mfma_f32_16x16x32_bf16 v[58:61], v[156:159], v[188:191], v[58:61]
	v_mfma_f32_16x16x32_bf16 v[46:49], v[148:151], v[196:199], v[46:49]
	v_mfma_f32_16x16x32_bf16 v[42:45], v[156:159], v[196:199], v[42:45]
	v_mfma_f32_16x16x32_bf16 v[30:33], v[148:151], v[204:207], v[30:33]
	v_mfma_f32_16x16x32_bf16 v[26:29], v[156:159], v[204:207], v[26:29]
	v_mfma_f32_16x16x32_bf16 v[14:17], v[148:151], v[212:215], v[14:17]
	v_mfma_f32_16x16x32_bf16 v[10:13], v[156:159], v[212:215], v[10:13]
	v_mfma_f32_16x16x32_bf16 v[62:65], v[152:155], v[192:195], v[62:65]
	v_mfma_f32_16x16x32_bf16 v[58:61], v[160:163], v[192:195], v[58:61]
	v_mfma_f32_16x16x32_bf16 v[46:49], v[152:155], v[200:203], v[46:49]
	v_mfma_f32_16x16x32_bf16 v[42:45], v[160:163], v[200:203], v[42:45]
	v_mfma_f32_16x16x32_bf16 v[30:33], v[152:155], v[208:211], v[30:33]
	v_mfma_f32_16x16x32_bf16 v[26:29], v[160:163], v[208:211], v[26:29]
	v_mfma_f32_16x16x32_bf16 v[14:17], v[152:155], v[216:219], v[14:17]
	v_mfma_f32_16x16x32_bf16 v[10:13], v[160:163], v[216:219], v[10:13]
	s_setprio 0
	s_setprio 1
	v_mfma_f32_16x16x32_bf16 v[54:57], v[164:167], v[188:191], v[54:57]
	v_mfma_f32_16x16x32_bf16 v[50:53], v[180:183], v[188:191], v[50:53]
	v_mfma_f32_16x16x32_bf16 v[38:41], v[164:167], v[196:199], v[38:41]
	v_mfma_f32_16x16x32_bf16 v[34:37], v[180:183], v[196:199], v[34:37]
	v_mfma_f32_16x16x32_bf16 v[22:25], v[164:167], v[204:207], v[22:25]
	v_mfma_f32_16x16x32_bf16 v[18:21], v[180:183], v[204:207], v[18:21]
	v_mfma_f32_16x16x32_bf16 v[6:9], v[164:167], v[212:215], v[6:9]
	v_mfma_f32_16x16x32_bf16 v[2:5], v[180:183], v[212:215], v[2:5]
	v_mfma_f32_16x16x32_bf16 v[54:57], v[176:179], v[192:195], v[54:57]
	v_mfma_f32_16x16x32_bf16 v[50:53], v[184:187], v[192:195], v[50:53]
	v_mfma_f32_16x16x32_bf16 v[38:41], v[176:179], v[200:203], v[38:41]
	v_mfma_f32_16x16x32_bf16 v[34:37], v[184:187], v[200:203], v[34:37]
	v_mfma_f32_16x16x32_bf16 v[22:25], v[176:179], v[208:211], v[22:25]
	v_mfma_f32_16x16x32_bf16 v[18:21], v[184:187], v[208:211], v[18:21]
	v_mfma_f32_16x16x32_bf16 v[6:9], v[176:179], v[216:219], v[6:9]
	v_mfma_f32_16x16x32_bf16 v[2:5], v[184:187], v[216:219], v[2:5]
	s_setprio 0
	s_barrier
; #define PG8_STAGE(bufoff, gbase, voff) do { _Pragma("unroll") for (int _i = 0; _i < 2; ++_i) \
;         __builtin_amdgcn_global_load_lds((const unsigned*)((const char*)(gbase) + (voff)[_i]), (PG8_LAS unsigned*)(lds + (bufoff) + ldsw + _i * 8192), 16, 0, 0); } while (0)
; #define PG8_LDA(dst, b, h) do { _Pragma("unroll") for (int m = 0; m < 4; ++m) _Pragma("unroll") for (int k = 0; k < 2; ++k) dst[m][k] = *(const PG8_LAS bf16x8*)(lds + PG8_SA(b, h) + aoff + m * 2048 + k * 1024); } while (0)
; #define PG8_LDB(dst, b, h) do { _Pragma("unroll") for (int n = 0; n < 2; ++n) _Pragma("unroll") for (int k = 0; k < 2; ++k) dst[n][k] = *(const PG8_LAS bf16x8*)(lds + PG8_SB(b, h) + boff + n * 2048 + k * 1024); } while (0)
; #define PG8_MMA(ai, bj, At, Bt) do { __builtin_amdgcn_s_setprio(1); _Pragma("unroll") for (int m = 0; m < 4; ++m) _Pragma("unroll") for (int n = 0; n < 2; ++n) _Pragma("unroll") for (int k = 0; k < 2; ++k) \
;         acc[ai][bj][m][n] = __builtin_amdgcn_mfma_f32_16x16x32_bf16(Bt[n][k], At[m][k], acc[ai][bj][m][n], 0, 0, 0); __builtin_amdgcn_s_setprio(0); } while (0)
; #define PG8_WAIT_V(n) asm volatile("s_waitcnt vmcnt(" #n ")" ::: "memory")
; #define PG8_WAIT_L(n) asm volatile("s_waitcnt lgkmcnt(" #n ")" ::: "memory")
; #define PG8_BAR __builtin_amdgcn_s_barrier()
; #define PG8_SCHED __builtin_amdgcn_sched_barrier(0)
; template <class Epi, class Sched, bool ALIGN_EPI = false, bool SP2 = false>
; __device__ __forceinline__ void gemm_phase(PG8_LAS unsigned char* lds, const Gemm g, const Sched& S, const Epi& E) {
;     ...
;             PG8_LDB(B0, 1, 0); PG8_LDB(B1, 1, 1); PG8_SCHED; PG8_LDA(At, 1, 0); PG8_STAGE(PG8_SA(0, 1), a2 + hstep, voffA);
;             PG8_WAIT_V(8); PG8_WAIT_L(0); PG8_BAR; PG8_MMA(0, 0, At, B0); PG8_MMA(0, 1, At, B1); PG8_BAR; PG8_SCHED;
	s_add_i32 s72, 0, 0x18000
	v_add_u32_e32 v138, s72, v168
	s_add_i32 s73, 0, 0x1c000
	ds_read_b128 v[148:151], v138
	ds_read_b128 v[152:155], v138 offset:1024
	ds_read_b128 v[156:159], v138 offset:2048
	ds_read_b128 v[160:163], v138 offset:3072
	v_add_u32_e32 v138, s73, v168
	ds_read_b128 v[164:167], v138
	ds_read_b128 v[176:179], v138 offset:1024
	ds_read_b128 v[180:183], v138 offset:2048
	ds_read_b128 v[184:187], v138 offset:3072
	s_add_u32 s8, s8, 0x18000
	s_addc_u32 s9, s9, 0
	s_mov_b32 m0, s45
	v_lshl_add_u64 v[228:229], s[8:9], 0, v[130:131]
	ds_read_b128 v[188:191], v174 offset:32768
	ds_read_b128 v[192:195], v174 offset:33792
	ds_read_b128 v[196:199], v174 offset:34816
	ds_read_b128 v[200:203], v174 offset:35840
	ds_read_b128 v[204:207], v174 offset:36864
	ds_read_b128 v[208:211], v174 offset:37888
	ds_read_b128 v[212:215], v174 offset:38912
	ds_read_b128 v[216:219], v174 offset:39936
	global_load_lds_dwordx4 v[228:229], off
	v_lshl_add_u64 v[228:229], s[8:9], 0, v[134:135]
	s_mov_b32 m0, s52
	s_nop 0
	global_load_lds_dwordx4 v[228:229], off
	s_waitcnt vmcnt(8)
	s_waitcnt lgkmcnt(0)
	s_barrier
	s_setprio 1
	s_waitcnt lgkmcnt(0)
	v_mfma_f32_16x16x32_bf16 v[126:129], v[148:151], v[188:191], v[126:129]
	v_mfma_f32_16x16x32_bf16 v[122:125], v[156:159], v[188:191], v[122:125]
	v_mfma_f32_16x16x32_bf16 v[110:113], v[148:151], v[196:199], v[110:113]
	v_mfma_f32_16x16x32_bf16 v[106:109], v[156:159], v[196:199], v[106:109]
	v_mfma_f32_16x16x32_bf16 v[94:97], v[148:151], v[204:207], v[94:97]
	v_mfma_f32_16x16x32_bf16 v[90:93], v[156:159], v[204:207], v[90:93]
	v_mfma_f32_16x16x32_bf16 v[78:81], v[148:151], v[212:215], v[78:81]
	v_mfma_f32_16x16x32_bf16 v[74:77], v[156:159], v[212:215], v[74:77]
	v_mfma_f32_16x16x32_bf16 v[126:129], v[152:155], v[192:195], v[126:129]
	v_mfma_f32_16x16x32_bf16 v[122:125], v[160:163], v[192:195], v[122:125]
	v_mfma_f32_16x16x32_bf16 v[110:113], v[152:155], v[200:203], v[110:113]
	v_mfma_f32_16x16x32_bf16 v[106:109], v[160:163], v[200:203], v[106:109]
	v_mfma_f32_16x16x32_bf16 v[94:97], v[152:155], v[208:211], v[94:97]
	v_mfma_f32_16x16x32_bf16 v[90:93], v[160:163], v[208:211], v[90:93]
	v_mfma_f32_16x16x32_bf16 v[78:81], v[152:155], v[216:219], v[78:81]
	v_mfma_f32_16x16x32_bf16 v[74:77], v[160:163], v[216:219], v[74:77]
	s_setprio 0
	s_setprio 1
	v_mfma_f32_16x16x32_bf16 v[118:121], v[164:167], v[188:191], v[118:121]
	v_mfma_f32_16x16x32_bf16 v[114:117], v[180:183], v[188:191], v[114:117]
	v_mfma_f32_16x16x32_bf16 v[102:105], v[164:167], v[196:199], v[102:105]
	v_mfma_f32_16x16x32_bf16 v[98:101], v[180:183], v[196:199], v[98:101]
	v_mfma_f32_16x16x32_bf16 v[86:89], v[164:167], v[204:207], v[86:89]
	v_mfma_f32_16x16x32_bf16 v[82:85], v[180:183], v[204:207], v[82:85]
	v_mfma_f32_16x16x32_bf16 v[70:73], v[164:167], v[212:215], v[70:73]
	v_mfma_f32_16x16x32_bf16 v[66:69], v[180:183], v[212:215], v[66:69]
	v_mfma_f32_16x16x32_bf16 v[118:121], v[176:179], v[192:195], v[118:121]
	v_mfma_f32_16x16x32_bf16 v[114:117], v[184:187], v[192:195], v[114:117]
	v_mfma_f32_16x16x32_bf16 v[102:105], v[176:179], v[200:203], v[102:105]
	v_mfma_f32_16x16x32_bf16 v[98:101], v[184:187], v[200:203], v[98:101]
	v_mfma_f32_16x16x32_bf16 v[86:89], v[176:179], v[208:211], v[86:89]
	v_mfma_f32_16x16x32_bf16 v[82:85], v[184:187], v[208:211], v[82:85]
	v_mfma_f32_16x16x32_bf16 v[70:73], v[176:179], v[216:219], v[70:73]
	v_mfma_f32_16x16x32_bf16 v[66:69], v[184:187], v[216:219], v[66:69]
	s_setprio 0
	s_barrier
; #define PG8_STAGE(bufoff, gbase, voff) do { _Pragma("unroll") for (int _i = 0; _i < 2; ++_i) \
;         __builtin_amdgcn_global_load_lds((const unsigned*)((const char*)(gbase) + (voff)[_i]), (PG8_LAS unsigned*)(lds + (bufoff) + ldsw + _i * 8192), 16, 0, 0); } while (0)
; #define PG8_LDA(dst, b, h) do { _Pragma("unroll") for (int m = 0; m < 4; ++m) _Pragma("unroll") for (int k = 0; k < 2; ++k) dst[m][k] = *(const PG8_LAS bf16x8*)(lds + PG8_SA(b, h) + aoff + m * 2048 + k * 1024); } while (0)
; #define PG8_MMA(ai, bj, At, Bt) do { __builtin_amdgcn_s_setprio(1); _Pragma("unroll") for (int m = 0; m < 4; ++m) _Pragma("unroll") for (int n = 0; n < 2; ++n) _Pragma("unroll") for (int k = 0; k < 2; ++k) \
;         acc[ai][bj][m][n] = __builtin_amdgcn_mfma_f32_16x16x32_bf16(Bt[n][k], At[m][k], acc[ai][bj][m][n], 0, 0, 0); __builtin_amdgcn_s_setprio(0); } while (0)
; #define PG8_WAIT_V(n) asm volatile("s_waitcnt vmcnt(" #n ")" ::: "memory")
; #define PG8_WAIT_L(n) asm volatile("s_waitcnt lgkmcnt(" #n ")" ::: "memory")
; #define PG8_BAR __builtin_amdgcn_s_barrier()
; #define PG8_SCHED __builtin_amdgcn_sched_barrier(0)
; template <class Epi, class Sched, bool ALIGN_EPI = false, bool SP2 = false>
; __device__ __forceinline__ void gemm_phase(PG8_LAS unsigned char* lds, const Gemm g, const Sched& S, const Epi& E) {
;     ...
;         for (int t = 0; t < nt; t += 2) {
;             const bool last = (t == nt - 2);
;     ...
;             PG8_LDA(At, 1, 1); PG8_STAGE(PG8_SB(1, 0), b3, voffB); PG8_STAGE(PG8_SB(1, 1), b3 + hstep, voffB); PG8_STAGE(PG8_SA(1, 0), a3, voffA);
;             PG8_WAIT_V(8); PG8_WAIT_L(0); PG8_BAR; PG8_MMA(1, 0, At, B0); PG8_MMA(1, 1, At, B1); PG8_BAR; PG8_SCHED;
	s_add_i32 s8, s72, s42
	v_lshl_add_u64 v[220:221], v[220:221], 0, s[14:15]
	s_mov_b32 m0, s8
	ds_read_b128 v[188:191], v174 offset:49152
	ds_read_b128 v[192:195], v174 offset:50176
	ds_read_b128 v[196:199], v174 offset:51200
	ds_read_b128 v[200:203], v174 offset:52224
	ds_read_b128 v[204:207], v174 offset:53248
	ds_read_b128 v[208:211], v174 offset:54272
	ds_read_b128 v[212:215], v174 offset:55296
	ds_read_b128 v[216:219], v174 offset:56320
	global_load_lds_dwordx4 v[220:221], off
	s_add_i32 m0, s8, 0x2000
	s_add_u32 s6, s6, 0x18080
	v_lshl_add_u64 v[220:221], v[222:223], 0, s[14:15]
	s_addc_u32 s7, s7, 0
	s_add_i32 s8, s73, s42
	global_load_lds_dwordx4 v[220:221], off
	v_lshl_add_u64 v[220:221], s[6:7], 0, v[132:133]
	s_mov_b32 m0, s8
	s_nop 0
	global_load_lds_dwordx4 v[220:221], off
	v_lshl_add_u64 v[220:221], s[6:7], 0, v[136:137]
	s_add_i32 m0, s8, 0x2000
	s_nop 0
	global_load_lds_dwordx4 v[220:221], off
	v_lshl_add_u64 v[220:221], v[224:225], 0, s[14:15]
	s_mov_b32 m0, s56
	s_nop 0
	global_load_lds_dwordx4 v[220:221], off
	v_lshl_add_u64 v[220:221], v[226:227], 0, s[14:15]
	s_mov_b32 m0, s57
	s_nop 0
	global_load_lds_dwordx4 v[220:221], off
	s_waitcnt vmcnt(8)
	s_waitcnt lgkmcnt(0)
	s_barrier
	s_setprio 1
	s_waitcnt lgkmcnt(0)
	v_mfma_f32_16x16x32_bf16 v[62:65], v[148:151], v[188:191], v[62:65]
	v_mfma_f32_16x16x32_bf16 v[58:61], v[156:159], v[188:191], v[58:61]
	v_mfma_f32_16x16x32_bf16 v[46:49], v[148:151], v[196:199], v[46:49]
	v_mfma_f32_16x16x32_bf16 v[42:45], v[156:159], v[196:199], v[42:45]
	v_mfma_f32_16x16x32_bf16 v[30:33], v[148:151], v[204:207], v[30:33]
	v_mfma_f32_16x16x32_bf16 v[26:29], v[156:159], v[204:207], v[26:29]
	v_mfma_f32_16x16x32_bf16 v[14:17], v[148:151], v[212:215], v[14:17]
	v_mfma_f32_16x16x32_bf16 v[10:13], v[156:159], v[212:215], v[10:13]
	v_mfma_f32_16x16x32_bf16 v[62:65], v[152:155], v[192:195], v[62:65]
	v_mfma_f32_16x16x32_bf16 v[58:61], v[160:163], v[192:195], v[58:61]
	v_mfma_f32_16x16x32_bf16 v[46:49], v[152:155], v[200:203], v[46:49]
	v_mfma_f32_16x16x32_bf16 v[42:45], v[160:163], v[200:203], v[42:45]
	v_mfma_f32_16x16x32_bf16 v[30:33], v[152:155], v[208:211], v[30:33]
	v_mfma_f32_16x16x32_bf16 v[26:29], v[160:163], v[208:211], v[26:29]
	v_mfma_f32_16x16x32_bf16 v[14:17], v[152:155], v[216:219], v[14:17]
	v_mfma_f32_16x16x32_bf16 v[10:13], v[160:163], v[216:219], v[10:13]
	s_setprio 0
	s_setprio 1
	v_mfma_f32_16x16x32_bf16 v[54:57], v[164:167], v[188:191], v[54:57]
	v_mfma_f32_16x16x32_bf16 v[50:53], v[180:183], v[188:191], v[50:53]
	v_mfma_f32_16x16x32_bf16 v[38:41], v[164:167], v[196:199], v[38:41]
	v_mfma_f32_16x16x32_bf16 v[34:37], v[180:183], v[196:199], v[34:37]
	v_mfma_f32_16x16x32_bf16 v[22:25], v[164:167], v[204:207], v[22:25]
	v_mfma_f32_16x16x32_bf16 v[18:21], v[180:183], v[204:207], v[18:21]
	v_mfma_f32_16x16x32_bf16 v[6:9], v[164:167], v[212:215], v[6:9]
	v_mfma_f32_16x16x32_bf16 v[2:5], v[180:183], v[212:215], v[2:5]
	v_mfma_f32_16x16x32_bf16 v[54:57], v[176:179], v[192:195], v[54:57]
	v_mfma_f32_16x16x32_bf16 v[50:53], v[184:187], v[192:195], v[50:53]
	v_mfma_f32_16x16x32_bf16 v[38:41], v[176:179], v[200:203], v[38:41]
	v_mfma_f32_16x16x32_bf16 v[34:37], v[184:187], v[200:203], v[34:37]
	v_mfma_f32_16x16x32_bf16 v[22:25], v[176:179], v[208:211], v[22:25]
	v_mfma_f32_16x16x32_bf16 v[18:21], v[184:187], v[208:211], v[18:21]
	v_mfma_f32_16x16x32_bf16 v[6:9], v[176:179], v[216:219], v[6:9]
	v_mfma_f32_16x16x32_bf16 v[2:5], v[184:187], v[216:219], v[2:5]
	s_setprio 0
	s_barrier
	s_add_i32 s71, s71, 2
	s_add_u32 s4, s4, 0x100
	s_addc_u32 s5, s5, 0
	s_add_u32 s35, s35, 0x100
	s_addc_u32 s70, s70, 0
	s_cmp_ge_i32 s71, s98
	s_cbranch_scc0 .LBB0_865
	s_and_b64 vcc, exec, s[16:17]
	s_cbranch_vccz .LBB0_868
	s_barrier

; __global__ void __launch_bounds__(NTHR, 2) mega(Args a) {
;     extern __shared__ __attribute__((aligned(16))) unsigned char lds_raw[];
	.amdhsa_kernel _Z4mega4Args
		.amdhsa_group_segment_fixed_size 0
		.amdhsa_private_segment_fixed_size 0
		.amdhsa_kernarg_size 512
		.amdhsa_user_sgpr_count 2
		.amdhsa_user_sgpr_dispatch_ptr 0
		.amdhsa_user_sgpr_queue_ptr 0
		.amdhsa_user_sgpr_kernarg_segment_ptr 1
		.amdhsa_user_sgpr_dispatch_id 0
		.amdhsa_user_sgpr_kernarg_preload_length 0
		.amdhsa_user_sgpr_kernarg_preload_offset 0
		.amdhsa_user_sgpr_private_segment_size 0
		.amdhsa_uses_dynamic_stack 0
		.amdhsa_enable_private_segment 0
		.amdhsa_system_sgpr_workgroup_id_x 1
		.amdhsa_system_sgpr_workgroup_id_y 0
		.amdhsa_system_sgpr_workgroup_id_z 0
		.amdhsa_system_sgpr_workgroup_info 0
		.amdhsa_system_vgpr_workitem_id 2
		.amdhsa_next_free_vgpr 233
		.amdhsa_next_free_sgpr 102
		.amdhsa_accum_offset 236
		.amdhsa_reserve_vcc 1
		.amdhsa_float_round_mode_32 0
		.amdhsa_float_round_mode_16_64 0
		.amdhsa_float_denorm_mode_32 3
		.amdhsa_float_denorm_mode_16_64 3
		.amdhsa_dx10_clamp 1
		.amdhsa_ieee_mode 1
		.amdhsa_fp16_overflow 0
		.amdhsa_tg_split 0
		.amdhsa_exception_fp_ieee_invalid_op 0
		.amdhsa_exception_fp_denorm_src 0
		.amdhsa_exception_fp_ieee_div_zero 0
		.amdhsa_exception_fp_ieee_overflow 0
		.amdhsa_exception_fp_ieee_underflow 0
		.amdhsa_exception_fp_ieee_inexact 0
		.amdhsa_exception_int_div_zero 0
	.end_amdhsa_kernel

; __global__ void __launch_bounds__(NTHR, 2) mega(Args a) {
;     extern __shared__ __attribute__((aligned(16))) unsigned char lds_raw[];
amdhsa.kernels:
  - .agpr_count:     0
    .args:
      - .offset:         0
        .size:           256
        .value_kind:     by_value
      - .offset:         256
        .size:           4
        .value_kind:     hidden_block_count_x
      - .offset:         260
        .size:           4
        .value_kind:     hidden_block_count_y
      - .offset:         264
        .size:           4
        .value_kind:     hidden_block_count_z
      - .offset:         268
        .size:           2
        .value_kind:     hidden_group_size_x
      - .offset:         270
        .size:           2
        .value_kind:     hidden_group_size_y
      - .offset:         272
        .size:           2
        .value_kind:     hidden_group_size_z
      - .offset:         274
        .size:           2
        .value_kind:     hidden_remainder_x
      - .offset:         276
        .size:           2
        .value_kind:     hidden_remainder_y
      - .offset:         278
        .size:           2
        .value_kind:     hidden_remainder_z
      - .offset:         296
        .size:           8
        .value_kind:     hidden_global_offset_x
      - .offset:         304
        .size:           8
        .value_kind:     hidden_global_offset_y
      - .offset:         312
        .size:           8
        .value_kind:     hidden_global_offset_z
      - .offset:         320
        .size:           2
        .value_kind:     hidden_grid_dims
      - .offset:         344
        .size:           8
        .value_kind:     hidden_multigrid_sync_arg
      - .offset:         376
        .size:           4
        .value_kind:     hidden_dynamic_lds_size
    .group_segment_fixed_size: 0
    .kernarg_segment_align: 8
    .kernarg_segment_size: 512
    .language:       OpenCL C
    .language_version:
      - 2
      - 0
    .max_flat_workgroup_size: 512
    .name:           _Z4mega4Args
    .private_segment_fixed_size: 0
    .sgpr_count:     108
    .sgpr_spill_count: 86
    .symbol:         _Z4mega4Args.kd
    .uniform_work_group_size: 1
    .uses_dynamic_stack: false
    .vgpr_count:     233
    .vgpr_spill_count: 0
    .wavefront_size: 64
